# prefill attention: waves 4-7 delayed by s_sleep 14 after each tile barrier (stagger the two waves of each SIMD)
# speedup vs baseline: 1.0102x; 1.0058x over previous
.LBB0_955:
	s_waitcnt lgkmcnt(0)
	s_barrier
	v_readlane_b32 s100, v255, 8
	s_cmp_lt_u32 s100, 4
	s_cbranch_scc1 .Lpf_nostag
	s_sleep 14
.Lpf_nostag:
	s_add_i32 s54, s54, 64
	s_cmp_eq_u32 s50, s62
	s_cbranch_scc1 .LBB0_957
	s_mov_b32 s2, s62
	s_branch .LBB0_931

	.amdhsa_kernel _Z8yoco_fwd4Args
		.amdhsa_group_segment_fixed_size 0
		.amdhsa_private_segment_fixed_size 0
		.amdhsa_kernarg_size 520
		.amdhsa_user_sgpr_count 2
		.amdhsa_user_sgpr_dispatch_ptr 0
		.amdhsa_user_sgpr_queue_ptr 0
		.amdhsa_user_sgpr_kernarg_segment_ptr 1
		.amdhsa_user_sgpr_dispatch_id 0
		.amdhsa_user_sgpr_kernarg_preload_length 0
		.amdhsa_user_sgpr_kernarg_preload_offset 0
		.amdhsa_user_sgpr_private_segment_size 0
		.amdhsa_uses_dynamic_stack 0
		.amdhsa_enable_private_segment 0
		.amdhsa_system_sgpr_workgroup_id_x 1
		.amdhsa_system_sgpr_workgroup_id_y 0
		.amdhsa_system_sgpr_workgroup_id_z 0
		.amdhsa_system_sgpr_workgroup_info 0
		.amdhsa_system_vgpr_workitem_id 0
		.amdhsa_next_free_vgpr 256
		.amdhsa_next_free_sgpr 102
		.amdhsa_accum_offset 256
		.amdhsa_reserve_vcc 1
		.amdhsa_float_round_mode_32 0
		.amdhsa_float_round_mode_16_64 0
		.amdhsa_float_denorm_mode_32 3
		.amdhsa_float_denorm_mode_16_64 3
		.amdhsa_dx10_clamp 1
		.amdhsa_ieee_mode 1
		.amdhsa_fp16_overflow 0
		.amdhsa_tg_split 0
		.amdhsa_exception_fp_ieee_invalid_op 0
		.amdhsa_exception_fp_denorm_src 0
		.amdhsa_exception_fp_ieee_div_zero 0
		.amdhsa_exception_fp_ieee_overflow 0
		.amdhsa_exception_fp_ieee_underflow 0
		.amdhsa_exception_fp_ieee_inexact 0
		.amdhsa_exception_int_div_zero 0
	.end_amdhsa_kernel

amdhsa.kernels:
  - .agpr_count:     0
    .args:
      - .offset:         0
        .size:           264
        .value_kind:     by_value
      - .offset:         264
        .size:           4
        .value_kind:     hidden_block_count_x
      - .offset:         268
        .size:           4
        .value_kind:     hidden_block_count_y
      - .offset:         272
        .size:           4
        .value_kind:     hidden_block_count_z
      - .offset:         276
        .size:           2
        .value_kind:     hidden_group_size_x
      - .offset:         278
        .size:           2
        .value_kind:     hidden_group_size_y
      - .offset:         280
        .size:           2
        .value_kind:     hidden_group_size_z
      - .offset:         282
        .size:           2
        .value_kind:     hidden_remainder_x
      - .offset:         284
        .size:           2
        .value_kind:     hidden_remainder_y
      - .offset:         286
        .size:           2
        .value_kind:     hidden_remainder_z
      - .offset:         304
        .size:           8
        .value_kind:     hidden_global_offset_x
      - .offset:         312
        .size:           8
        .value_kind:     hidden_global_offset_y
      - .offset:         320
        .size:           8
        .value_kind:     hidden_global_offset_z
      - .offset:         328
        .size:           2
        .value_kind:     hidden_grid_dims
      - .offset:         384
        .size:           4
        .value_kind:     hidden_dynamic_lds_size
    .group_segment_fixed_size: 0
    .kernarg_segment_align: 8
    .kernarg_segment_size: 520
    .language:       OpenCL C
    .language_version:
      - 2
      - 0
    .max_flat_workgroup_size: 512
    .name:           _Z8yoco_fwd4Args
    .private_segment_fixed_size: 0
    .sgpr_count:     108
    .sgpr_spill_count: 69
    .symbol:         _Z8yoco_fwd4Args.kd
    .uniform_work_group_size: 1
    .uses_dynamic_stack: false
    .vgpr_count:     256
    .vgpr_spill_count: 0
    .wavefront_size: 64
